# PH4: next-layer weight conversion tiles moved from the scan CU-mate to the 256 attention/pool workers (after their own items)
# speedup vs baseline: 1.0178x; 1.0037x over previous
.LBB0_765:
	s_or_b64 exec, exec, s[0:1]
	v_readlane_b32 s0, v208, 60
	v_readlane_b32 s1, v208, 61
	s_cmp_eq_u32 s0, 3
	s_mov_b32 s4, s0
	s_cselect_b64 s[0:1], -1, 0
	v_readlane_b32 s2, v208, 24
	v_writelane_b32 v207, s0, 0
	s_cmp_eq_u32 s2, 0
	s_waitcnt lgkmcnt(0)
	v_writelane_b32 v207, s1, 1
	s_cselect_b64 s[0:1], -1, 0
	s_waitcnt vmcnt(0)
	v_cndmask_b32_e64 v0, 0, 1, s[0:1]
	v_readlane_b32 s0, v208, 0
	s_cmp_gt_i32 s2, -1
	v_readlane_b32 s1, v208, 1
	s_barrier
	s_nop 0
	v_cndmask_b32_e64 v2, 0, 1, s[0:1]
	s_cselect_b64 s[0:1], -1, 0
	v_writelane_b32 v207, s0, 5
	s_nop 1
	v_cndmask_b32_e64 v0, v2, v0, s[0:1]
	v_writelane_b32 v207, s1, 6
	v_and_b32_e32 v0, 1, v0
	s_add_i32 s0, s4, 1
	v_writelane_b32 v207, s0, 7
	v_cmp_eq_u32_e32 vcc, 0, v0
	s_nop 0
	v_writelane_b32 v207, s1, 8
	s_mov_b64 s[0:1], -1
	s_cbranch_vccz .LBB0_1063
	v_readlane_b32 s0, v207, 0
	v_readlane_b32 s1, v207, 1
	s_and_b64 s[0:1], s[0:1], exec
	s_cselect_b32 s0, 0, 0x5c0
	v_writelane_b32 v207, s0, 9
	v_readlane_b32 s0, v208, 24
	s_cmp_lg_u32 s0, 1
	s_mov_b64 s[0:1], -1
	s_cbranch_scc0 .LBB0_1029
	v_readlane_b32 s4, v207, 5
	v_readlane_b32 s5, v207, 6
	s_and_b64 s[0:1], s[4:5], exec
	v_readlane_b32 s0, v208, 2
	v_readlane_b32 s1, v208, 26
	s_cselect_b32 s9, s1, s0
	v_readlane_b32 s0, v207, 9
	s_add_i32 s2, s0, 0x550
	s_and_b64 s[0:1], s[4:5], exec
	s_mov_b32 s0, s2
	s_nop 0
	s_cmp_ge_i32 s9, s0
	v_writelane_b32 v207, s0, 2
	s_cbranch_scc1 .LBB0_1028
	v_readlane_b32 s0, v207, 5
	v_readlane_b32 s1, v207, 6
	s_and_b64 s[0:1], s[0:1], exec
	v_readlane_b32 s0, v208, 3
	s_cselect_b32 s0, 0x100, s0
	v_readlane_b32 s34, v208, 60
	v_writelane_b32 v207, s0, 3
	v_readlane_b32 s44, v210, 50
	v_readlane_b32 s6, v207, 7
	v_readlane_b32 s7, v207, 8
	s_mov_b32 s8, s6
	s_bitcmp1_b32 s6, 0
	s_mov_b32 s7, s11
	v_writelane_b32 v207, s8, 7
	s_cselect_b32 s4, 0x1700000, 0
	s_lshl_b64 s[0:1], s[6:7], 24
	s_lshl_b64 s[2:3], s[6:7], 22
	v_writelane_b32 v207, s9, 8
	s_lshl_b32 s7, s34, 8
	v_writelane_b32 v207, s7, 10
	s_lshl_b32 s7, s34, 2
	v_writelane_b32 v207, s7, 11
	s_add_u32 s7, s84, s0
	v_writelane_b32 v207, s7, 12
	s_addc_u32 s7, s85, s1
	v_readlane_b32 s54, v210, 60
	v_writelane_b32 v207, s7, 13
	v_readlane_b32 s55, v210, 61
	s_add_u32 s7, s54, s4
	v_writelane_b32 v207, s7, 14
	s_addc_u32 s7, s55, 0
	v_writelane_b32 v207, s7, 15
	s_add_u32 s0, s82, s0
	v_readlane_b32 s52, v210, 58
	v_writelane_b32 v207, s0, 16
	s_addc_u32 s0, s83, s1
	v_readlane_b32 s45, v210, 51
	v_readlane_b32 s46, v210, 52
	v_readlane_b32 s47, v210, 53
	v_readlane_b32 s48, v210, 54
	v_readlane_b32 s49, v210, 55
	v_readlane_b32 s50, v210, 56
	v_readlane_b32 s51, v210, 57
	v_readlane_b32 s53, v210, 59
	v_readlane_b32 s56, v210, 62
	v_readlane_b32 s57, v210, 63
	v_readlane_b32 s58, v209, 0
	v_readlane_b32 s59, v209, 1
	v_writelane_b32 v207, s0, 17
	s_add_u32 s0, s52, s4
	v_writelane_b32 v207, s0, 18
	s_addc_u32 s0, s53, 0
	v_readlane_b32 s44, v210, 18
	v_readlane_b32 s46, v210, 20
	v_readlane_b32 s48, v210, 22
	v_readlane_b32 s49, v210, 23
	v_readlane_b32 s50, v210, 24
	v_readlane_b32 s51, v210, 25
	v_readlane_b32 s52, v210, 26
	v_readlane_b32 s53, v210, 27
	v_readlane_b32 s54, v210, 28
	v_readlane_b32 s55, v210, 29
	v_readlane_b32 s56, v210, 30
	v_readlane_b32 s57, v210, 31
	v_readlane_b32 s58, v210, 32
	v_readlane_b32 s59, v210, 33
	v_writelane_b32 v207, s0, 19
	v_readlane_b32 s47, v210, 21
	s_add_u32 s0, s46, s2
	v_readlane_b32 s48, v210, 50
	v_writelane_b32 v207, s0, 20
	s_addc_u32 s0, s47, s3
	v_readlane_b32 s49, v210, 51
	v_readlane_b32 s50, v210, 52
	v_readlane_b32 s51, v210, 53
	v_readlane_b32 s52, v210, 54
	v_readlane_b32 s53, v210, 55
	v_readlane_b32 s54, v210, 56
	v_readlane_b32 s55, v210, 57
	v_readlane_b32 s56, v210, 58
	v_readlane_b32 s57, v210, 59
	v_readlane_b32 s58, v210, 60
	v_readlane_b32 s59, v210, 61
	v_readlane_b32 s60, v210, 62
	v_readlane_b32 s61, v210, 63
	v_readlane_b32 s62, v209, 0
	v_readlane_b32 s63, v209, 1
	v_writelane_b32 v207, s0, 21
	s_add_u32 s0, s54, s4
	v_readlane_b32 s48, v210, 50
	v_readlane_b32 s55, v210, 57
	s_mul_hi_u32 s5, s6, 0x9c0000
	s_mul_i32 s6, s6, 0x9c0000
	v_writelane_b32 v207, s0, 22
	s_addc_u32 s2, s55, 0
	v_readlane_b32 s45, v210, 19
	v_readlane_b32 s49, v210, 51
	v_readlane_b32 s50, v210, 52
	v_readlane_b32 s51, v210, 53
	v_writelane_b32 v207, s2, 23
	s_add_u32 s2, s44, s6
	v_readlane_b32 s60, v210, 62
	v_readlane_b32 s61, v210, 63
	v_readlane_b32 s62, v209, 0
	v_readlane_b32 s63, v209, 1
	v_writelane_b32 v207, s2, 24
	s_addc_u32 s2, s45, s5
	v_readlane_b32 s36, v210, 50
	v_readlane_b32 s54, v210, 56
	v_readlane_b32 s0, v208, 51
	v_readlane_b32 s60, v209, 3
	v_readlane_b32 s40, v210, 54
	v_readlane_b32 s52, v210, 54
	v_readlane_b32 s53, v210, 55
	v_readlane_b32 s56, v210, 58
	v_readlane_b32 s57, v210, 59
	v_readlane_b32 s58, v210, 60
	v_readlane_b32 s59, v210, 61
	v_readlane_b32 s1, v208, 52
	v_readlane_b32 s67, v209, 10
	v_writelane_b32 v207, s2, 25
	v_readlane_b32 s54, v209, 14
	v_readlane_b32 s41, v210, 55
	v_readlane_b32 s42, v210, 56
	v_readlane_b32 s43, v210, 57
	s_add_u32 s2, s40, s4
	s_movk_i32 s53, 0x2000
	s_movk_i32 s52, 0x2200
	s_movk_i32 s59, 0x70
	s_mov_b32 s58, 0x30000
	s_mov_b32 s57, 0x20000
	s_mov_b32 s56, 0x10000
	v_readlane_b32 s61, v209, 4
	v_readlane_b32 s62, v209, 5
	v_readlane_b32 s63, v209, 6
	v_readlane_b32 s64, v209, 7
	v_readlane_b32 s65, v209, 8
	v_readlane_b32 s66, v209, 9
	s_mov_b32 s67, 0x3a000
	v_readlane_b32 s55, v209, 15
	v_writelane_b32 v207, s2, 26
	s_mov_b64 s[42:43], s[0:1]
	s_addc_u32 s0, s41, 0
	s_mov_b32 s8, s9
	v_readlane_b32 s35, v208, 61
	v_readlane_b32 s37, v210, 51
	v_readlane_b32 s38, v210, 52
	v_readlane_b32 s39, v210, 53
	v_readlane_b32 s44, v210, 58
	v_readlane_b32 s45, v210, 59
	v_readlane_b32 s46, v210, 60
	v_readlane_b32 s47, v210, 61
	v_readlane_b32 s48, v210, 62
	v_readlane_b32 s49, v210, 63
	v_readlane_b32 s50, v209, 0
	v_readlane_b32 s51, v209, 1
	v_writelane_b32 v207, s0, 27
	s_branch .LBB0_771

.LBB0_1029:
	s_andn2_b64 vcc, exec, s[0:1]
	s_cbranch_vccnz .LBB0_1062
	v_readlane_b32 s0, v208, 26
	v_readlane_b32 s1, v207, 9
	s_cmp_eq_u32 s0, s0
	s_cbranch_scc1 .LBB0_1062
	v_readlane_b32 s4, v207, 7
	v_readlane_b32 s5, v207, 8
	s_bitcmp1_b32 s4, 0
	s_mov_b32 s5, s11
	s_cselect_b32 s10, 0x1700000, 0
	s_lshl_b64 s[0:1], s[4:5], 24
	s_lshl_b64 s[2:3], s[4:5], 22
	s_mul_hi_u32 s40, s4, 0x9c0000
	s_mov_b32 s6, s4
	s_mul_i32 s39, s4, 0x9c0000
	s_add_u32 s4, s84, s0
	v_readlane_b32 s44, v210, 50
	v_writelane_b32 v207, s6, 7
	s_addc_u32 s5, s85, s1
	v_readlane_b32 s54, v210, 60
	v_writelane_b32 v207, s7, 8
	v_readlane_b32 s55, v210, 61
	s_add_u32 s6, s54, s10
	s_addc_u32 s7, s55, 0
	s_add_u32 s8, s82, s0
	v_readlane_b32 s52, v210, 58
	v_readlane_b32 s58, v209, 0
	v_readlane_b32 s59, v209, 1
	s_addc_u32 s9, s83, s1
	v_readlane_b32 s45, v210, 51
	v_readlane_b32 s46, v210, 52
	v_readlane_b32 s47, v210, 53
	v_readlane_b32 s48, v210, 54
	v_readlane_b32 s49, v210, 55
	v_readlane_b32 s50, v210, 56
	v_readlane_b32 s51, v210, 57
	v_readlane_b32 s53, v210, 59
	v_readlane_b32 s56, v210, 62
	v_readlane_b32 s57, v210, 63
	s_add_u32 s33, s52, s10
	s_mov_b64 s[86:87], s[58:59]
	s_addc_u32 s34, s53, 0
	s_mov_b64 s[84:85], s[56:57]
	s_mov_b64 s[82:83], s[54:55]
	s_mov_b64 s[80:81], s[52:53]
	s_mov_b64 s[78:79], s[50:51]
	s_mov_b64 s[76:77], s[48:49]
	s_mov_b64 s[74:75], s[46:47]
	s_mov_b64 s[72:73], s[44:45]
	v_readlane_b32 s44, v210, 18
	v_readlane_b32 s46, v210, 20
	v_readlane_b32 s47, v210, 21
	s_add_u32 s35, s46, s2
	s_addc_u32 s36, s47, s3
	s_add_u32 s37, s78, s10
	s_addc_u32 s38, s79, 0
	v_readlane_b32 s45, v210, 19
	s_add_u32 s39, s44, s39
	s_addc_u32 s40, s45, s40
	v_readlane_b32 s56, v210, 30
	v_readlane_b32 s57, v210, 31
	v_readlane_b32 s58, v210, 32
	s_add_u32 s41, s76, s10
	v_readlane_b32 s46, v208, 26
	s_mov_b32 s58, 0x30000
	s_mov_b32 s57, 0x20000
	s_mov_b32 s56, 0x10000
	s_addc_u32 s42, s77, 0
	s_lshl_b32 s43, s46, 6
	s_lshl_b32 s44, s46, 3
	s_lshl_b32 s45, s46, 1
	v_readlane_b32 s47, v207, 9
	v_readlane_b32 s48, v210, 22
	v_readlane_b32 s49, v210, 23
	v_readlane_b32 s50, v210, 24
	v_readlane_b32 s51, v210, 25
	v_readlane_b32 s52, v210, 26
	v_readlane_b32 s53, v210, 27
	v_readlane_b32 s54, v210, 28
	v_readlane_b32 s55, v210, 29
	v_readlane_b32 s59, v210, 33
	s_branch .LBB0_1034
